# GEMM K-loop heads aligned to 64 bytes (s_nop padding), otherwise identical to the previous best
# speedup vs baseline: 1.0026x; 1.0026x over previous
;     ...
;         const bool has_next = S.next(ui + 1, nxt);
;         const char* nA = has_next ? (const char*)g.A + (size_t)nxt.pm * tstep : cA; const char* nB = has_next ? (const char*)g.Bt + (size_t)nxt.pn * tstep : cB;
;     ...
; #pragma unroll
;         for (int a = 0; a < 2; ++a)
; #pragma unroll
;             for (int b = 0; b < 2; ++b)
; #pragma unroll
;                 for (int m = 0; m < 4; ++m)
; #pragma unroll
;                     for (int n = 0; n < 2; ++n) acc[a][b][m][n] = (f32x4){0.f, 0.f, 0.f, 0.f};
;         cur = nxt; cA = nA; cB = nB; ++ui;
.LBB0_231:
	s_ashr_i32 s19, s18, 31
	s_lshl_b64 s[20:21], s[18:19], 19
	s_add_u32 s20, s29, s20
	s_addc_u32 s21, s42, s21
	s_and_b64 s[22:23], s[4:5], exec
	s_cselect_b32 s19, s21, s39
	s_cselect_b32 s58, s20, s38
	s_ashr_i32 s15, s14, 31
	s_lshl_b64 s[22:23], s[14:15], 19
	s_add_u32 s22, s43, s22
	s_addc_u32 s23, s44, s23
	s_and_b64 s[34:35], s[4:5], exec
	s_cselect_b32 s15, s23, s37
	s_cselect_b32 s59, s22, s36
	s_add_u32 s60, s36, 0x100
	s_addc_u32 s61, s37, 0
	s_add_u32 s36, s38, 0x40080
	v_mov_b32_e32 v0, 0
	s_addc_u32 s37, s39, 0
	s_mov_b32 s62, -2
	v_mov_b32_e32 v1, v0
	v_mov_b32_e32 v2, v0
	v_mov_b32_e32 v3, v0
	v_mov_b32_e32 v4, v0
	v_mov_b32_e32 v5, v0
	v_mov_b32_e32 v6, v0
	v_mov_b32_e32 v7, v0
	v_mov_b32_e32 v16, v0
	v_mov_b32_e32 v17, v0
	v_mov_b32_e32 v18, v0
	v_mov_b32_e32 v19, v0
	v_mov_b32_e32 v20, v0
	v_mov_b32_e32 v21, v0
	v_mov_b32_e32 v22, v0
	v_mov_b32_e32 v23, v0
	v_mov_b32_e32 v32, v0
	v_mov_b32_e32 v33, v0
	v_mov_b32_e32 v34, v0
	v_mov_b32_e32 v35, v0
	v_mov_b32_e32 v36, v0
	v_mov_b32_e32 v37, v0
	v_mov_b32_e32 v38, v0
	v_mov_b32_e32 v39, v0
	v_mov_b32_e32 v48, v0
	v_mov_b32_e32 v49, v0
	v_mov_b32_e32 v50, v0
	v_mov_b32_e32 v51, v0
	v_mov_b32_e32 v52, v0
	v_mov_b32_e32 v53, v0
	v_mov_b32_e32 v54, v0
	v_mov_b32_e32 v55, v0
	v_mov_b32_e32 v8, v0
	v_mov_b32_e32 v9, v0
	v_mov_b32_e32 v10, v0
	v_mov_b32_e32 v11, v0
	v_mov_b32_e32 v12, v0
	v_mov_b32_e32 v13, v0
	v_mov_b32_e32 v14, v0
	v_mov_b32_e32 v15, v0
	v_mov_b32_e32 v24, v0
	v_mov_b32_e32 v25, v0
	v_mov_b32_e32 v26, v0
	v_mov_b32_e32 v27, v0
	v_mov_b32_e32 v28, v0
	v_mov_b32_e32 v29, v0
	v_mov_b32_e32 v30, v0
	v_mov_b32_e32 v31, v0
	v_mov_b32_e32 v40, v0
	v_mov_b32_e32 v41, v0
	v_mov_b32_e32 v42, v0
	v_mov_b32_e32 v43, v0
	v_mov_b32_e32 v44, v0
	v_mov_b32_e32 v45, v0
	v_mov_b32_e32 v46, v0
	v_mov_b32_e32 v47, v0
	v_mov_b32_e32 v56, v0
	v_mov_b32_e32 v57, v0
	v_mov_b32_e32 v58, v0
	v_mov_b32_e32 v59, v0
	v_mov_b32_e32 v60, v0
	v_mov_b32_e32 v61, v0
	v_mov_b32_e32 v62, v0
	v_mov_b32_e32 v63, v0
	v_mov_b32_e32 v64, v0
	v_mov_b32_e32 v65, v0
	v_mov_b32_e32 v66, v0
	v_mov_b32_e32 v67, v0
	v_mov_b32_e32 v68, v0
	v_mov_b32_e32 v69, v0
	v_mov_b32_e32 v70, v0
	v_mov_b32_e32 v71, v0
	v_mov_b32_e32 v80, v0
	v_mov_b32_e32 v81, v0
	v_mov_b32_e32 v82, v0
	v_mov_b32_e32 v83, v0
	v_mov_b32_e32 v84, v0
	v_mov_b32_e32 v85, v0
	v_mov_b32_e32 v86, v0
	v_mov_b32_e32 v87, v0
	v_mov_b32_e32 v96, v0
	v_mov_b32_e32 v97, v0
	v_mov_b32_e32 v98, v0
	v_mov_b32_e32 v99, v0
	v_mov_b32_e32 v100, v0
	v_mov_b32_e32 v101, v0
	v_mov_b32_e32 v102, v0
	v_mov_b32_e32 v103, v0
	v_mov_b32_e32 v112, v0
	v_mov_b32_e32 v113, v0
	v_mov_b32_e32 v114, v0
	v_mov_b32_e32 v115, v0
	v_mov_b32_e32 v116, v0
	v_mov_b32_e32 v117, v0
	v_mov_b32_e32 v118, v0
	v_mov_b32_e32 v119, v0
	v_mov_b32_e32 v72, v0
	v_mov_b32_e32 v73, v0
	v_mov_b32_e32 v74, v0
	v_mov_b32_e32 v75, v0
	v_mov_b32_e32 v76, v0
	v_mov_b32_e32 v77, v0
	v_mov_b32_e32 v78, v0
	v_mov_b32_e32 v79, v0
	v_mov_b32_e32 v88, v0
	v_mov_b32_e32 v89, v0
	v_mov_b32_e32 v90, v0
	v_mov_b32_e32 v91, v0
	v_mov_b32_e32 v92, v0
	v_mov_b32_e32 v93, v0
	v_mov_b32_e32 v94, v0
	v_mov_b32_e32 v95, v0
	v_mov_b32_e32 v104, v0
	v_mov_b32_e32 v105, v0
	v_mov_b32_e32 v106, v0
	v_mov_b32_e32 v107, v0
	v_mov_b32_e32 v108, v0
	v_mov_b32_e32 v109, v0
	v_mov_b32_e32 v110, v0
	v_mov_b32_e32 v111, v0
	v_mov_b32_e32 v120, v0
	v_mov_b32_e32 v121, v0
	v_mov_b32_e32 v122, v0
	v_mov_b32_e32 v123, v0
	v_mov_b32_e32 v124, v0
	v_mov_b32_e32 v125, v0
	v_mov_b32_e32 v126, v0
	v_mov_b32_e32 v127, v0
	.p2alignl 6, 3212836864

;     ...
; #pragma unroll
;         for (int a = 0; a < 2; ++a)
; #pragma unroll
;             for (int b = 0; b < 2; ++b)
; #pragma unroll
;                 for (int m = 0; m < 4; ++m)
; #pragma unroll
;                     for (int n = 0; n < 2; ++n) acc[a][b][m][n] = (f32x4){0.f, 0.f, 0.f, 0.f};
;         cur = nxt; cA = nA; cB = nB; ++ui;
.LBB0_311:
	s_add_u32 s67, s36, 0x100
	v_mov_b32_e32 v0, 0
	s_addc_u32 s68, s37, 0
	s_mov_b32 s69, -2
	v_mov_b32_e32 v1, v0
	v_mov_b32_e32 v2, v0
	v_mov_b32_e32 v3, v0
	v_mov_b32_e32 v4, v0
	v_mov_b32_e32 v5, v0
	v_mov_b32_e32 v6, v0
	v_mov_b32_e32 v7, v0
	v_mov_b32_e32 v12, v0
	v_mov_b32_e32 v13, v0
	v_mov_b32_e32 v14, v0
	v_mov_b32_e32 v15, v0
	v_mov_b32_e32 v20, v0
	v_mov_b32_e32 v21, v0
	v_mov_b32_e32 v22, v0
	v_mov_b32_e32 v23, v0
	v_mov_b32_e32 v28, v0
	v_mov_b32_e32 v29, v0
	v_mov_b32_e32 v30, v0
	v_mov_b32_e32 v31, v0
	v_mov_b32_e32 v36, v0
	v_mov_b32_e32 v37, v0
	v_mov_b32_e32 v38, v0
	v_mov_b32_e32 v39, v0
	v_mov_b32_e32 v44, v0
	v_mov_b32_e32 v45, v0
	v_mov_b32_e32 v46, v0
	v_mov_b32_e32 v47, v0
	v_mov_b32_e32 v52, v0
	v_mov_b32_e32 v53, v0
	v_mov_b32_e32 v54, v0
	v_mov_b32_e32 v55, v0
	v_mov_b32_e32 v8, v0
	v_mov_b32_e32 v9, v0
	v_mov_b32_e32 v10, v0
	v_mov_b32_e32 v11, v0
	v_mov_b32_e32 v16, v0
	v_mov_b32_e32 v17, v0
	v_mov_b32_e32 v18, v0
	v_mov_b32_e32 v19, v0
	v_mov_b32_e32 v24, v0
	v_mov_b32_e32 v25, v0
	v_mov_b32_e32 v26, v0
	v_mov_b32_e32 v27, v0
	v_mov_b32_e32 v32, v0
	v_mov_b32_e32 v33, v0
	v_mov_b32_e32 v34, v0
	v_mov_b32_e32 v35, v0
	v_mov_b32_e32 v40, v0
	v_mov_b32_e32 v41, v0
	v_mov_b32_e32 v42, v0
	v_mov_b32_e32 v43, v0
	v_mov_b32_e32 v48, v0
	v_mov_b32_e32 v49, v0
	v_mov_b32_e32 v50, v0
	v_mov_b32_e32 v51, v0
	v_mov_b32_e32 v56, v0
	v_mov_b32_e32 v57, v0
	v_mov_b32_e32 v58, v0
	v_mov_b32_e32 v59, v0
	v_mov_b32_e32 v60, v0
	v_mov_b32_e32 v61, v0
	v_mov_b32_e32 v62, v0
	v_mov_b32_e32 v63, v0
	v_mov_b32_e32 v64, v0
	v_mov_b32_e32 v65, v0
	v_mov_b32_e32 v66, v0
	v_mov_b32_e32 v67, v0
	v_mov_b32_e32 v68, v0
	v_mov_b32_e32 v69, v0
	v_mov_b32_e32 v70, v0
	v_mov_b32_e32 v71, v0
	v_mov_b32_e32 v76, v0
	v_mov_b32_e32 v77, v0
	v_mov_b32_e32 v78, v0
	v_mov_b32_e32 v79, v0
	v_mov_b32_e32 v84, v0
	v_mov_b32_e32 v85, v0
	v_mov_b32_e32 v86, v0
	v_mov_b32_e32 v87, v0
	v_mov_b32_e32 v92, v0
	v_mov_b32_e32 v93, v0
	v_mov_b32_e32 v94, v0
	v_mov_b32_e32 v95, v0
	v_mov_b32_e32 v100, v0
	v_mov_b32_e32 v101, v0
	v_mov_b32_e32 v102, v0
	v_mov_b32_e32 v103, v0
	v_mov_b32_e32 v108, v0
	v_mov_b32_e32 v109, v0
	v_mov_b32_e32 v110, v0
	v_mov_b32_e32 v111, v0
	v_mov_b32_e32 v116, v0
	v_mov_b32_e32 v117, v0
	v_mov_b32_e32 v118, v0
	v_mov_b32_e32 v119, v0
	v_mov_b32_e32 v72, v0
	v_mov_b32_e32 v73, v0
	v_mov_b32_e32 v74, v0
	v_mov_b32_e32 v75, v0
	v_mov_b32_e32 v80, v0
	v_mov_b32_e32 v81, v0
	v_mov_b32_e32 v82, v0
	v_mov_b32_e32 v83, v0
	v_mov_b32_e32 v88, v0
	v_mov_b32_e32 v89, v0
	v_mov_b32_e32 v90, v0
	v_mov_b32_e32 v91, v0
	v_mov_b32_e32 v96, v0
	v_mov_b32_e32 v97, v0
	v_mov_b32_e32 v98, v0
	v_mov_b32_e32 v99, v0
	v_mov_b32_e32 v104, v0
	v_mov_b32_e32 v105, v0
	v_mov_b32_e32 v106, v0
	v_mov_b32_e32 v107, v0
	v_mov_b32_e32 v112, v0
	v_mov_b32_e32 v113, v0
	v_mov_b32_e32 v114, v0
	v_mov_b32_e32 v115, v0
	v_mov_b32_e32 v120, v0
	v_mov_b32_e32 v121, v0
	v_mov_b32_e32 v122, v0
	v_mov_b32_e32 v123, v0
	v_mov_b32_e32 v124, v0
	v_mov_b32_e32 v125, v0
	v_mov_b32_e32 v126, v0
	v_mov_b32_e32 v127, v0
	.p2alignl 6, 3212836864

;     ...
;         const bool has_next = S.next(ui + 1, nxt);
;         const char* nA = has_next ? (const char*)g.A + (size_t)nxt.pm * tstep : cA; const char* nB = has_next ? (const char*)g.Bt + (size_t)nxt.pn * tstep : cB;
;     ...
; #pragma unroll
;         for (int a = 0; a < 2; ++a)
; #pragma unroll
;             for (int b = 0; b < 2; ++b)
; #pragma unroll
;                 for (int m = 0; m < 4; ++m)
; #pragma unroll
;                     for (int n = 0; n < 2; ++n) acc[a][b][m][n] = (f32x4){0.f, 0.f, 0.f, 0.f};
;         cur = nxt; cA = nA; cB = nB; ++ui;
.LBB0_453:
	s_ashr_i32 s61, s60, 31
	s_lshl_b64 s[6:7], s[60:61], 19
	s_add_u32 s62, s3, s6
	s_addc_u32 s63, s29, s7
	s_and_b64 s[6:7], s[10:11], exec
	s_cselect_b32 s6, s63, s69
	s_cselect_b32 s7, s62, s68
	s_ashr_i32 s59, s58, 31
	s_lshl_b64 s[34:35], s[58:59], 19
	s_add_u32 s64, s72, s34
	s_addc_u32 s65, s73, s35
	s_and_b64 s[34:35], s[10:11], exec
	s_cselect_b32 s15, s65, s13
	s_cselect_b32 s22, s64, s12
	s_add_u32 s59, s12, 0x100
	s_addc_u32 s61, s13, 0
	s_add_u32 s12, s68, 0x40080
	v_mov_b32_e32 v0, 0
	s_addc_u32 s13, s69, 0
	s_mov_b32 s67, -2
	v_mov_b32_e32 v1, v0
	v_mov_b32_e32 v2, v0
	v_mov_b32_e32 v3, v0
	v_mov_b32_e32 v4, v0
	v_mov_b32_e32 v5, v0
	v_mov_b32_e32 v6, v0
	v_mov_b32_e32 v7, v0
	v_mov_b32_e32 v16, v0
	v_mov_b32_e32 v17, v0
	v_mov_b32_e32 v18, v0
	v_mov_b32_e32 v19, v0
	v_mov_b32_e32 v20, v0
	v_mov_b32_e32 v21, v0
	v_mov_b32_e32 v22, v0
	v_mov_b32_e32 v23, v0
	v_mov_b32_e32 v32, v0
	v_mov_b32_e32 v33, v0
	v_mov_b32_e32 v34, v0
	v_mov_b32_e32 v35, v0
	v_mov_b32_e32 v36, v0
	v_mov_b32_e32 v37, v0
	v_mov_b32_e32 v38, v0
	v_mov_b32_e32 v39, v0
	v_mov_b32_e32 v48, v0
	v_mov_b32_e32 v49, v0
	v_mov_b32_e32 v50, v0
	v_mov_b32_e32 v51, v0
	v_mov_b32_e32 v52, v0
	v_mov_b32_e32 v53, v0
	v_mov_b32_e32 v54, v0
	v_mov_b32_e32 v55, v0
	v_mov_b32_e32 v8, v0
	v_mov_b32_e32 v9, v0
	v_mov_b32_e32 v10, v0
	v_mov_b32_e32 v11, v0
	v_mov_b32_e32 v12, v0
	v_mov_b32_e32 v13, v0
	v_mov_b32_e32 v14, v0
	v_mov_b32_e32 v15, v0
	v_mov_b32_e32 v24, v0
	v_mov_b32_e32 v25, v0
	v_mov_b32_e32 v26, v0
	v_mov_b32_e32 v27, v0
	v_mov_b32_e32 v28, v0
	v_mov_b32_e32 v29, v0
	v_mov_b32_e32 v30, v0
	v_mov_b32_e32 v31, v0
	v_mov_b32_e32 v40, v0
	v_mov_b32_e32 v41, v0
	v_mov_b32_e32 v42, v0
	v_mov_b32_e32 v43, v0
	v_mov_b32_e32 v44, v0
	v_mov_b32_e32 v45, v0
	v_mov_b32_e32 v46, v0
	v_mov_b32_e32 v47, v0
	v_mov_b32_e32 v56, v0
	v_mov_b32_e32 v57, v0
	v_mov_b32_e32 v58, v0
	v_mov_b32_e32 v59, v0
	v_mov_b32_e32 v60, v0
	v_mov_b32_e32 v61, v0
	v_mov_b32_e32 v62, v0
	v_mov_b32_e32 v63, v0
	v_mov_b32_e32 v64, v0
	v_mov_b32_e32 v65, v0
	v_mov_b32_e32 v66, v0
	v_mov_b32_e32 v67, v0
	v_mov_b32_e32 v68, v0
	v_mov_b32_e32 v69, v0
	v_mov_b32_e32 v70, v0
	v_mov_b32_e32 v71, v0
	v_mov_b32_e32 v80, v0
	v_mov_b32_e32 v81, v0
	v_mov_b32_e32 v82, v0
	v_mov_b32_e32 v83, v0
	v_mov_b32_e32 v84, v0
	v_mov_b32_e32 v85, v0
	v_mov_b32_e32 v86, v0
	v_mov_b32_e32 v87, v0
	v_mov_b32_e32 v96, v0
	v_mov_b32_e32 v97, v0
	v_mov_b32_e32 v98, v0
	v_mov_b32_e32 v99, v0
	v_mov_b32_e32 v100, v0
	v_mov_b32_e32 v101, v0
	v_mov_b32_e32 v102, v0
	v_mov_b32_e32 v103, v0
	v_mov_b32_e32 v112, v0
	v_mov_b32_e32 v113, v0
	v_mov_b32_e32 v114, v0
	v_mov_b32_e32 v115, v0
	v_mov_b32_e32 v116, v0
	v_mov_b32_e32 v117, v0
	v_mov_b32_e32 v118, v0
	v_mov_b32_e32 v119, v0
	v_mov_b32_e32 v72, v0
	v_mov_b32_e32 v73, v0
	v_mov_b32_e32 v74, v0
	v_mov_b32_e32 v75, v0
	v_mov_b32_e32 v76, v0
	v_mov_b32_e32 v77, v0
	v_mov_b32_e32 v78, v0
	v_mov_b32_e32 v79, v0
	v_mov_b32_e32 v88, v0
	v_mov_b32_e32 v89, v0
	v_mov_b32_e32 v90, v0
	v_mov_b32_e32 v91, v0
	v_mov_b32_e32 v92, v0
	v_mov_b32_e32 v93, v0
	v_mov_b32_e32 v94, v0
	v_mov_b32_e32 v95, v0
	v_mov_b32_e32 v104, v0
	v_mov_b32_e32 v105, v0
	v_mov_b32_e32 v106, v0
	v_mov_b32_e32 v107, v0
	v_mov_b32_e32 v108, v0
	v_mov_b32_e32 v109, v0
	v_mov_b32_e32 v110, v0
	v_mov_b32_e32 v111, v0
	v_mov_b32_e32 v120, v0
	v_mov_b32_e32 v121, v0
	v_mov_b32_e32 v122, v0
	v_mov_b32_e32 v123, v0
	v_mov_b32_e32 v124, v0
	v_mov_b32_e32 v125, v0
	v_mov_b32_e32 v126, v0
	v_mov_b32_e32 v127, v0
	.p2alignl 6, 3212836864

;     ...
;         const bool has_next = S.next(ui + 1, nxt);
;         const char* nA = has_next ? (const char*)g.A + (size_t)nxt.pm * tstep : cA; const char* nB = has_next ? (const char*)g.Bt + (size_t)nxt.pn * tstep : cB;
;     ...
; #pragma unroll
;         for (int a = 0; a < 2; ++a)
; #pragma unroll
;             for (int b = 0; b < 2; ++b)
; #pragma unroll
;                 for (int m = 0; m < 4; ++m)
; #pragma unroll
;                     for (int n = 0; n < 2; ++n) acc[a][b][m][n] = (f32x4){0.f, 0.f, 0.f, 0.f};
;         cur = nxt; cA = nA; cB = nB; ++ui;
.LBB0_1122:
	s_ashr_i32 s27, s26, 31
	s_lshl_b64 s[8:9], s[26:27], 19
	s_add_u32 s36, s50, s8
	s_addc_u32 s37, s51, s9
	s_and_b64 s[8:9], s[10:11], exec
	s_cselect_b32 s7, s37, s43
	s_cselect_b32 s8, s36, s42
	s_ashr_i32 s23, s22, 31
	s_lshl_b64 s[16:17], s[22:23], 19
	s_add_u32 s38, s52, s16
	s_addc_u32 s39, s53, s17
	s_and_b64 s[16:17], s[10:11], exec
	s_cselect_b32 s9, s39, s45
	s_cselect_b32 s23, s38, s44
	s_add_u32 s27, s44, 0x100
	v_mov_b32_e32 v0, 0
	s_addc_u32 s70, s45, 0
	s_mov_b32 s71, -2
	v_mov_b32_e32 v1, v0
	v_mov_b32_e32 v2, v0
	v_mov_b32_e32 v3, v0
	v_mov_b32_e32 v4, v0
	v_mov_b32_e32 v5, v0
	v_mov_b32_e32 v6, v0
	v_mov_b32_e32 v7, v0
	v_mov_b32_e32 v16, v0
	v_mov_b32_e32 v17, v0
	v_mov_b32_e32 v18, v0
	v_mov_b32_e32 v19, v0
	v_mov_b32_e32 v20, v0
	v_mov_b32_e32 v21, v0
	v_mov_b32_e32 v22, v0
	v_mov_b32_e32 v23, v0
	v_mov_b32_e32 v32, v0
	v_mov_b32_e32 v33, v0
	v_mov_b32_e32 v34, v0
	v_mov_b32_e32 v35, v0
	v_mov_b32_e32 v36, v0
	v_mov_b32_e32 v37, v0
	v_mov_b32_e32 v38, v0
	v_mov_b32_e32 v39, v0
	v_mov_b32_e32 v48, v0
	v_mov_b32_e32 v49, v0
	v_mov_b32_e32 v50, v0
	v_mov_b32_e32 v51, v0
	v_mov_b32_e32 v52, v0
	v_mov_b32_e32 v53, v0
	v_mov_b32_e32 v54, v0
	v_mov_b32_e32 v55, v0
	v_mov_b32_e32 v8, v0
	v_mov_b32_e32 v9, v0
	v_mov_b32_e32 v10, v0
	v_mov_b32_e32 v11, v0
	v_mov_b32_e32 v12, v0
	v_mov_b32_e32 v13, v0
	v_mov_b32_e32 v14, v0
	v_mov_b32_e32 v15, v0
	v_mov_b32_e32 v24, v0
	v_mov_b32_e32 v25, v0
	v_mov_b32_e32 v26, v0
	v_mov_b32_e32 v27, v0
	v_mov_b32_e32 v28, v0
	v_mov_b32_e32 v29, v0
	v_mov_b32_e32 v30, v0
	v_mov_b32_e32 v31, v0
	v_mov_b32_e32 v40, v0
	v_mov_b32_e32 v41, v0
	v_mov_b32_e32 v42, v0
	v_mov_b32_e32 v43, v0
	v_mov_b32_e32 v44, v0
	v_mov_b32_e32 v45, v0
	v_mov_b32_e32 v46, v0
	v_mov_b32_e32 v47, v0
	v_mov_b32_e32 v56, v0
	v_mov_b32_e32 v57, v0
	v_mov_b32_e32 v58, v0
	v_mov_b32_e32 v59, v0
	v_mov_b32_e32 v60, v0
	v_mov_b32_e32 v61, v0
	v_mov_b32_e32 v62, v0
	v_mov_b32_e32 v63, v0
	v_mov_b32_e32 v64, v0
	v_mov_b32_e32 v65, v0
	v_mov_b32_e32 v66, v0
	v_mov_b32_e32 v67, v0
	v_mov_b32_e32 v68, v0
	v_mov_b32_e32 v69, v0
	v_mov_b32_e32 v70, v0
	v_mov_b32_e32 v71, v0
	v_mov_b32_e32 v80, v0
	v_mov_b32_e32 v81, v0
	v_mov_b32_e32 v82, v0
	v_mov_b32_e32 v83, v0
	v_mov_b32_e32 v84, v0
	v_mov_b32_e32 v85, v0
	v_mov_b32_e32 v86, v0
	v_mov_b32_e32 v87, v0
	v_mov_b32_e32 v96, v0
	v_mov_b32_e32 v97, v0
	v_mov_b32_e32 v98, v0
	v_mov_b32_e32 v99, v0
	v_mov_b32_e32 v100, v0
	v_mov_b32_e32 v101, v0
	v_mov_b32_e32 v102, v0
	v_mov_b32_e32 v103, v0
	v_mov_b32_e32 v112, v0
	v_mov_b32_e32 v113, v0
	v_mov_b32_e32 v114, v0
	v_mov_b32_e32 v115, v0
	v_mov_b32_e32 v116, v0
	v_mov_b32_e32 v117, v0
	v_mov_b32_e32 v118, v0
	v_mov_b32_e32 v119, v0
	v_mov_b32_e32 v72, v0
	v_mov_b32_e32 v73, v0
	v_mov_b32_e32 v74, v0
	v_mov_b32_e32 v75, v0
	v_mov_b32_e32 v76, v0
	v_mov_b32_e32 v77, v0
	v_mov_b32_e32 v78, v0
	v_mov_b32_e32 v79, v0
	v_mov_b32_e32 v88, v0
	v_mov_b32_e32 v89, v0
	v_mov_b32_e32 v90, v0
	v_mov_b32_e32 v91, v0
	v_mov_b32_e32 v92, v0
	v_mov_b32_e32 v93, v0
	v_mov_b32_e32 v94, v0
	v_mov_b32_e32 v95, v0
	v_mov_b32_e32 v104, v0
	v_mov_b32_e32 v105, v0
	v_mov_b32_e32 v106, v0
	v_mov_b32_e32 v107, v0
	v_mov_b32_e32 v108, v0
	v_mov_b32_e32 v109, v0
	v_mov_b32_e32 v110, v0
	v_mov_b32_e32 v111, v0
	v_mov_b32_e32 v120, v0
	v_mov_b32_e32 v121, v0
	v_mov_b32_e32 v122, v0
	v_mov_b32_e32 v123, v0
	v_mov_b32_e32 v124, v0
	v_mov_b32_e32 v125, v0
	v_mov_b32_e32 v126, v0
	v_mov_b32_e32 v127, v0
	.p2alignl 6, 3212836864

;     ...
;         const bool has_next = S.next(ui + 1, nxt);
;         const char* nA = has_next ? (const char*)g.A + (size_t)nxt.pm * tstep : cA; const char* nB = has_next ? (const char*)g.Bt + (size_t)nxt.pn * tstep : cB;
;     ...
; #pragma unroll
;         for (int a = 0; a < 2; ++a)
; #pragma unroll
;             for (int b = 0; b < 2; ++b)
; #pragma unroll
;                 for (int m = 0; m < 4; ++m)
; #pragma unroll
;                     for (int n = 0; n < 2; ++n) acc[a][b][m][n] = (f32x4){0.f, 0.f, 0.f, 0.f};
;         cur = nxt; cA = nA; cB = nB; ++ui;
.LBB0_1262:
	s_ashr_i32 s27, s26, 31
	s_lshl_b64 s[8:9], s[26:27], 19
	s_add_u32 s36, s48, s8
	s_addc_u32 s37, s49, s9
	s_and_b64 s[8:9], s[12:13], exec
	s_cselect_b32 s7, s37, s45
	s_cselect_b32 s8, s36, s44
	s_ashr_i32 s23, s22, 31
	s_lshl_b64 s[34:35], s[22:23], 19
	s_add_u32 s38, s50, s34
	s_addc_u32 s39, s51, s35
	s_and_b64 s[34:35], s[12:13], exec
	s_cselect_b32 s9, s39, s43
	s_cselect_b32 s23, s38, s42
	s_add_u32 s27, s42, 0x100
	s_addc_u32 s63, s43, 0
	s_add_u32 s42, s44, 0x40080
	v_mov_b32_e32 v0, 0
	s_addc_u32 s43, s45, 0
	s_mov_b32 s64, -2
	v_mov_b32_e32 v1, v0
	v_mov_b32_e32 v2, v0
	v_mov_b32_e32 v3, v0
	v_mov_b32_e32 v4, v0
	v_mov_b32_e32 v5, v0
	v_mov_b32_e32 v6, v0
	v_mov_b32_e32 v7, v0
	v_mov_b32_e32 v16, v0
	v_mov_b32_e32 v17, v0
	v_mov_b32_e32 v18, v0
	v_mov_b32_e32 v19, v0
	v_mov_b32_e32 v20, v0
	v_mov_b32_e32 v21, v0
	v_mov_b32_e32 v22, v0
	v_mov_b32_e32 v23, v0
	v_mov_b32_e32 v32, v0
	v_mov_b32_e32 v33, v0
	v_mov_b32_e32 v34, v0
	v_mov_b32_e32 v35, v0
	v_mov_b32_e32 v36, v0
	v_mov_b32_e32 v37, v0
	v_mov_b32_e32 v38, v0
	v_mov_b32_e32 v39, v0
	v_mov_b32_e32 v48, v0
	v_mov_b32_e32 v49, v0
	v_mov_b32_e32 v50, v0
	v_mov_b32_e32 v51, v0
	v_mov_b32_e32 v52, v0
	v_mov_b32_e32 v53, v0
	v_mov_b32_e32 v54, v0
	v_mov_b32_e32 v55, v0
	v_mov_b32_e32 v8, v0
	v_mov_b32_e32 v9, v0
	v_mov_b32_e32 v10, v0
	v_mov_b32_e32 v11, v0
	v_mov_b32_e32 v12, v0
	v_mov_b32_e32 v13, v0
	v_mov_b32_e32 v14, v0
	v_mov_b32_e32 v15, v0
	v_mov_b32_e32 v24, v0
	v_mov_b32_e32 v25, v0
	v_mov_b32_e32 v26, v0
	v_mov_b32_e32 v27, v0
	v_mov_b32_e32 v28, v0
	v_mov_b32_e32 v29, v0
	v_mov_b32_e32 v30, v0
	v_mov_b32_e32 v31, v0
	v_mov_b32_e32 v40, v0
	v_mov_b32_e32 v41, v0
	v_mov_b32_e32 v42, v0
	v_mov_b32_e32 v43, v0
	v_mov_b32_e32 v44, v0
	v_mov_b32_e32 v45, v0
	v_mov_b32_e32 v46, v0
	v_mov_b32_e32 v47, v0
	v_mov_b32_e32 v56, v0
	v_mov_b32_e32 v57, v0
	v_mov_b32_e32 v58, v0
	v_mov_b32_e32 v59, v0
	v_mov_b32_e32 v60, v0
	v_mov_b32_e32 v61, v0
	v_mov_b32_e32 v62, v0
	v_mov_b32_e32 v63, v0
	v_mov_b32_e32 v64, v0
	v_mov_b32_e32 v65, v0
	v_mov_b32_e32 v66, v0
	v_mov_b32_e32 v67, v0
	v_mov_b32_e32 v68, v0
	v_mov_b32_e32 v69, v0
	v_mov_b32_e32 v70, v0
	v_mov_b32_e32 v71, v0
	v_mov_b32_e32 v80, v0
	v_mov_b32_e32 v81, v0
	v_mov_b32_e32 v82, v0
	v_mov_b32_e32 v83, v0
	v_mov_b32_e32 v84, v0
	v_mov_b32_e32 v85, v0
	v_mov_b32_e32 v86, v0
	v_mov_b32_e32 v87, v0
	v_mov_b32_e32 v96, v0
	v_mov_b32_e32 v97, v0
	v_mov_b32_e32 v98, v0
	v_mov_b32_e32 v99, v0
	v_mov_b32_e32 v100, v0
	v_mov_b32_e32 v101, v0
	v_mov_b32_e32 v102, v0
	v_mov_b32_e32 v103, v0
	v_mov_b32_e32 v112, v0
	v_mov_b32_e32 v113, v0
	v_mov_b32_e32 v114, v0
	v_mov_b32_e32 v115, v0
	v_mov_b32_e32 v116, v0
	v_mov_b32_e32 v117, v0
	v_mov_b32_e32 v118, v0
	v_mov_b32_e32 v119, v0
	v_mov_b32_e32 v72, v0
	v_mov_b32_e32 v73, v0
	v_mov_b32_e32 v74, v0
	v_mov_b32_e32 v75, v0
	v_mov_b32_e32 v76, v0
	v_mov_b32_e32 v77, v0
	v_mov_b32_e32 v78, v0
	v_mov_b32_e32 v79, v0
	v_mov_b32_e32 v88, v0
	v_mov_b32_e32 v89, v0
	v_mov_b32_e32 v90, v0
	v_mov_b32_e32 v91, v0
	v_mov_b32_e32 v92, v0
	v_mov_b32_e32 v93, v0
	v_mov_b32_e32 v94, v0
	v_mov_b32_e32 v95, v0
	v_mov_b32_e32 v104, v0
	v_mov_b32_e32 v105, v0
	v_mov_b32_e32 v106, v0
	v_mov_b32_e32 v107, v0
	v_mov_b32_e32 v108, v0
	v_mov_b32_e32 v109, v0
	v_mov_b32_e32 v110, v0
	v_mov_b32_e32 v111, v0
	v_mov_b32_e32 v120, v0
	v_mov_b32_e32 v121, v0
	v_mov_b32_e32 v122, v0
	v_mov_b32_e32 v123, v0
	v_mov_b32_e32 v124, v0
	v_mov_b32_e32 v125, v0
	v_mov_b32_e32 v126, v0
	v_mov_b32_e32 v127, v0
	.p2alignl 6, 3212836864

;     ...
; #pragma unroll
;         for (int a = 0; a < 2; ++a)
; #pragma unroll
;             for (int b = 0; b < 2; ++b)
; #pragma unroll
;                 for (int m = 0; m < 4; ++m)
; #pragma unroll
;                     for (int n = 0; n < 2; ++n) acc[a][b][m][n] = (f32x4){0.f, 0.f, 0.f, 0.f};
;         cur = nxt; cA = nA; cB = nB; ++ui;
.LBB0_1342:
	s_add_u32 s8, s38, 0x100
	v_mov_b32_e32 v0, 0
	s_addc_u32 s9, s39, 0
	s_mov_b32 s67, -2
	v_mov_b32_e32 v1, v0
	v_mov_b32_e32 v2, v0
	v_mov_b32_e32 v3, v0
	v_mov_b32_e32 v4, v0
	v_mov_b32_e32 v5, v0
	v_mov_b32_e32 v6, v0
	v_mov_b32_e32 v7, v0
	v_mov_b32_e32 v16, v0
	v_mov_b32_e32 v17, v0
	v_mov_b32_e32 v18, v0
	v_mov_b32_e32 v19, v0
	v_mov_b32_e32 v20, v0
	v_mov_b32_e32 v21, v0
	v_mov_b32_e32 v22, v0
	v_mov_b32_e32 v23, v0
	v_mov_b32_e32 v32, v0
	v_mov_b32_e32 v33, v0
	v_mov_b32_e32 v34, v0
	v_mov_b32_e32 v35, v0
	v_mov_b32_e32 v36, v0
	v_mov_b32_e32 v37, v0
	v_mov_b32_e32 v38, v0
	v_mov_b32_e32 v39, v0
	v_mov_b32_e32 v48, v0
	v_mov_b32_e32 v49, v0
	v_mov_b32_e32 v50, v0
	v_mov_b32_e32 v51, v0
	v_mov_b32_e32 v52, v0
	v_mov_b32_e32 v53, v0
	v_mov_b32_e32 v54, v0
	v_mov_b32_e32 v55, v0
	v_mov_b32_e32 v8, v0
	v_mov_b32_e32 v9, v0
	v_mov_b32_e32 v10, v0
	v_mov_b32_e32 v11, v0
	v_mov_b32_e32 v12, v0
	v_mov_b32_e32 v13, v0
	v_mov_b32_e32 v14, v0
	v_mov_b32_e32 v15, v0
	v_mov_b32_e32 v24, v0
	v_mov_b32_e32 v25, v0
	v_mov_b32_e32 v26, v0
	v_mov_b32_e32 v27, v0
	v_mov_b32_e32 v28, v0
	v_mov_b32_e32 v29, v0
	v_mov_b32_e32 v30, v0
	v_mov_b32_e32 v31, v0
	v_mov_b32_e32 v40, v0
	v_mov_b32_e32 v41, v0
	v_mov_b32_e32 v42, v0
	v_mov_b32_e32 v43, v0
	v_mov_b32_e32 v44, v0
	v_mov_b32_e32 v45, v0
	v_mov_b32_e32 v46, v0
	v_mov_b32_e32 v47, v0
	v_mov_b32_e32 v56, v0
	v_mov_b32_e32 v57, v0
	v_mov_b32_e32 v58, v0
	v_mov_b32_e32 v59, v0
	v_mov_b32_e32 v60, v0
	v_mov_b32_e32 v61, v0
	v_mov_b32_e32 v62, v0
	v_mov_b32_e32 v63, v0
	v_mov_b32_e32 v64, v0
	v_mov_b32_e32 v65, v0
	v_mov_b32_e32 v66, v0
	v_mov_b32_e32 v67, v0
	v_mov_b32_e32 v68, v0
	v_mov_b32_e32 v69, v0
	v_mov_b32_e32 v70, v0
	v_mov_b32_e32 v71, v0
	v_mov_b32_e32 v80, v0
	v_mov_b32_e32 v81, v0
	v_mov_b32_e32 v82, v0
	v_mov_b32_e32 v83, v0
	v_mov_b32_e32 v84, v0
	v_mov_b32_e32 v85, v0
	v_mov_b32_e32 v86, v0
	v_mov_b32_e32 v87, v0
	v_mov_b32_e32 v96, v0
	v_mov_b32_e32 v97, v0
	v_mov_b32_e32 v98, v0
	v_mov_b32_e32 v99, v0
	v_mov_b32_e32 v100, v0
	v_mov_b32_e32 v101, v0
	v_mov_b32_e32 v102, v0
	v_mov_b32_e32 v103, v0
	v_mov_b32_e32 v112, v0
	v_mov_b32_e32 v113, v0
	v_mov_b32_e32 v114, v0
	v_mov_b32_e32 v115, v0
	v_mov_b32_e32 v116, v0
	v_mov_b32_e32 v117, v0
	v_mov_b32_e32 v118, v0
	v_mov_b32_e32 v119, v0
	v_mov_b32_e32 v72, v0
	v_mov_b32_e32 v73, v0
	v_mov_b32_e32 v74, v0
	v_mov_b32_e32 v75, v0
	v_mov_b32_e32 v76, v0
	v_mov_b32_e32 v77, v0
	v_mov_b32_e32 v78, v0
	v_mov_b32_e32 v79, v0
	v_mov_b32_e32 v88, v0
	v_mov_b32_e32 v89, v0
	v_mov_b32_e32 v90, v0
	v_mov_b32_e32 v91, v0
	v_mov_b32_e32 v92, v0
	v_mov_b32_e32 v93, v0
	v_mov_b32_e32 v94, v0
	v_mov_b32_e32 v95, v0
	v_mov_b32_e32 v104, v0
	v_mov_b32_e32 v105, v0
	v_mov_b32_e32 v106, v0
	v_mov_b32_e32 v107, v0
	v_mov_b32_e32 v108, v0
	v_mov_b32_e32 v109, v0
	v_mov_b32_e32 v110, v0
	v_mov_b32_e32 v111, v0
	v_mov_b32_e32 v120, v0
	v_mov_b32_e32 v121, v0
	v_mov_b32_e32 v122, v0
	v_mov_b32_e32 v123, v0
	v_mov_b32_e32 v124, v0
	v_mov_b32_e32 v125, v0
	v_mov_b32_e32 v126, v0
	v_mov_b32_e32 v127, v0
	.p2alignl 6, 3212836864

;     ...
;         const bool has_next = S.next(ui + 1, nxt);
;         const char* nA = has_next ? (const char*)g.A + (size_t)nxt.pm * tstep : cA; const char* nB = has_next ? (const char*)g.Bt + (size_t)nxt.pn * tstep : cB;
;     ...
; #pragma unroll
;         for (int a = 0; a < 2; ++a)
; #pragma unroll
;             for (int b = 0; b < 2; ++b)
; #pragma unroll
;                 for (int m = 0; m < 4; ++m)
; #pragma unroll
;                     for (int n = 0; n < 2; ++n) acc[a][b][m][n] = (f32x4){0.f, 0.f, 0.f, 0.f};
;         cur = nxt; cA = nA; cB = nB; ++ui;
.LBB0_1482:
	s_ashr_i32 s23, s22, 31
	s_lshl_b64 s[8:9], s[22:23], 19
	s_add_u32 s26, s46, s8
	s_addc_u32 s27, s47, s9
	s_and_b64 s[8:9], s[10:11], exec
	s_cselect_b32 s7, s27, s43
	s_cselect_b32 s8, s26, s42
	s_ashr_i32 s21, s20, 31
	s_lshl_b64 s[34:35], s[20:21], 19
	s_add_u32 s36, s48, s34
	s_addc_u32 s37, s49, s35
	s_and_b64 s[34:35], s[10:11], exec
	s_cselect_b32 s9, s37, s41
	s_cselect_b32 s21, s36, s40
	s_add_u32 s23, s40, 0x100
	s_addc_u32 s61, s41, 0
	s_add_u32 s40, s42, 0x40080
	v_mov_b32_e32 v0, 0
	s_addc_u32 s41, s43, 0
	s_mov_b32 s62, -2
	v_mov_b32_e32 v1, v0
	v_mov_b32_e32 v2, v0
	v_mov_b32_e32 v3, v0
	v_mov_b32_e32 v4, v0
	v_mov_b32_e32 v5, v0
	v_mov_b32_e32 v6, v0
	v_mov_b32_e32 v7, v0
	v_mov_b32_e32 v16, v0
	v_mov_b32_e32 v17, v0
	v_mov_b32_e32 v18, v0
	v_mov_b32_e32 v19, v0
	v_mov_b32_e32 v20, v0
	v_mov_b32_e32 v21, v0
	v_mov_b32_e32 v22, v0
	v_mov_b32_e32 v23, v0
	v_mov_b32_e32 v32, v0
	v_mov_b32_e32 v33, v0
	v_mov_b32_e32 v34, v0
	v_mov_b32_e32 v35, v0
	v_mov_b32_e32 v36, v0
	v_mov_b32_e32 v37, v0
	v_mov_b32_e32 v38, v0
	v_mov_b32_e32 v39, v0
	v_mov_b32_e32 v48, v0
	v_mov_b32_e32 v49, v0
	v_mov_b32_e32 v50, v0
	v_mov_b32_e32 v51, v0
	v_mov_b32_e32 v52, v0
	v_mov_b32_e32 v53, v0
	v_mov_b32_e32 v54, v0
	v_mov_b32_e32 v55, v0
	v_mov_b32_e32 v8, v0
	v_mov_b32_e32 v9, v0
	v_mov_b32_e32 v10, v0
	v_mov_b32_e32 v11, v0
	v_mov_b32_e32 v12, v0
	v_mov_b32_e32 v13, v0
	v_mov_b32_e32 v14, v0
	v_mov_b32_e32 v15, v0
	v_mov_b32_e32 v24, v0
	v_mov_b32_e32 v25, v0
	v_mov_b32_e32 v26, v0
	v_mov_b32_e32 v27, v0
	v_mov_b32_e32 v28, v0
	v_mov_b32_e32 v29, v0
	v_mov_b32_e32 v30, v0
	v_mov_b32_e32 v31, v0
	v_mov_b32_e32 v40, v0
	v_mov_b32_e32 v41, v0
	v_mov_b32_e32 v42, v0
	v_mov_b32_e32 v43, v0
	v_mov_b32_e32 v44, v0
	v_mov_b32_e32 v45, v0
	v_mov_b32_e32 v46, v0
	v_mov_b32_e32 v47, v0
	v_mov_b32_e32 v56, v0
	v_mov_b32_e32 v57, v0
	v_mov_b32_e32 v58, v0
	v_mov_b32_e32 v59, v0
	v_mov_b32_e32 v60, v0
	v_mov_b32_e32 v61, v0
	v_mov_b32_e32 v62, v0
	v_mov_b32_e32 v63, v0
	v_mov_b32_e32 v64, v0
	v_mov_b32_e32 v65, v0
	v_mov_b32_e32 v66, v0
	v_mov_b32_e32 v67, v0
	v_mov_b32_e32 v68, v0
	v_mov_b32_e32 v69, v0
	v_mov_b32_e32 v70, v0
	v_mov_b32_e32 v71, v0
	v_mov_b32_e32 v80, v0
	v_mov_b32_e32 v81, v0
	v_mov_b32_e32 v82, v0
	v_mov_b32_e32 v83, v0
	v_mov_b32_e32 v84, v0
	v_mov_b32_e32 v85, v0
	v_mov_b32_e32 v86, v0
	v_mov_b32_e32 v87, v0
	v_mov_b32_e32 v96, v0
	v_mov_b32_e32 v97, v0
	v_mov_b32_e32 v98, v0
	v_mov_b32_e32 v99, v0
	v_mov_b32_e32 v100, v0
	v_mov_b32_e32 v101, v0
	v_mov_b32_e32 v102, v0
	v_mov_b32_e32 v103, v0
	v_mov_b32_e32 v112, v0
	v_mov_b32_e32 v113, v0
	v_mov_b32_e32 v114, v0
	v_mov_b32_e32 v115, v0
	v_mov_b32_e32 v116, v0
	v_mov_b32_e32 v117, v0
	v_mov_b32_e32 v118, v0
	v_mov_b32_e32 v119, v0
	v_mov_b32_e32 v72, v0
	v_mov_b32_e32 v73, v0
	v_mov_b32_e32 v74, v0
	v_mov_b32_e32 v75, v0
	v_mov_b32_e32 v76, v0
	v_mov_b32_e32 v77, v0
	v_mov_b32_e32 v78, v0
	v_mov_b32_e32 v79, v0
	v_mov_b32_e32 v88, v0
	v_mov_b32_e32 v89, v0
	v_mov_b32_e32 v90, v0
	v_mov_b32_e32 v91, v0
	v_mov_b32_e32 v92, v0
	v_mov_b32_e32 v93, v0
	v_mov_b32_e32 v94, v0
	v_mov_b32_e32 v95, v0
	v_mov_b32_e32 v104, v0
	v_mov_b32_e32 v105, v0
	v_mov_b32_e32 v106, v0
	v_mov_b32_e32 v107, v0
	v_mov_b32_e32 v108, v0
	v_mov_b32_e32 v109, v0
	v_mov_b32_e32 v110, v0
	v_mov_b32_e32 v111, v0
	v_mov_b32_e32 v120, v0
	v_mov_b32_e32 v121, v0
	v_mov_b32_e32 v122, v0
	v_mov_b32_e32 v123, v0
	v_mov_b32_e32 v124, v0
	v_mov_b32_e32 v125, v0
	v_mov_b32_e32 v126, v0
	v_mov_b32_e32 v127, v0
	.p2alignl 6, 3212836864

;     ...
; #pragma unroll
;         for (int a = 0; a < 2; ++a)
; #pragma unroll
;             for (int b = 0; b < 2; ++b)
; #pragma unroll
;                 for (int m = 0; m < 4; ++m)
; #pragma unroll
;                     for (int n = 0; n < 2; ++n) acc[a][b][m][n] = (f32x4){0.f, 0.f, 0.f, 0.f};
;         cur = nxt; cA = nA; cB = nB; ++ui;
.LBB0_1562:
	s_add_u32 s8, s36, 0x100
	v_mov_b32_e32 v0, 0
	s_addc_u32 s9, s37, 0
	s_mov_b32 s65, -2
	v_mov_b32_e32 v1, v0
	v_mov_b32_e32 v2, v0
	v_mov_b32_e32 v3, v0
	v_mov_b32_e32 v4, v0
	v_mov_b32_e32 v5, v0
	v_mov_b32_e32 v6, v0
	v_mov_b32_e32 v7, v0
	v_mov_b32_e32 v16, v0
	v_mov_b32_e32 v17, v0
	v_mov_b32_e32 v18, v0
	v_mov_b32_e32 v19, v0
	v_mov_b32_e32 v20, v0
	v_mov_b32_e32 v21, v0
	v_mov_b32_e32 v22, v0
	v_mov_b32_e32 v23, v0
	v_mov_b32_e32 v32, v0
	v_mov_b32_e32 v33, v0
	v_mov_b32_e32 v34, v0
	v_mov_b32_e32 v35, v0
	v_mov_b32_e32 v36, v0
	v_mov_b32_e32 v37, v0
	v_mov_b32_e32 v38, v0
	v_mov_b32_e32 v39, v0
	v_mov_b32_e32 v48, v0
	v_mov_b32_e32 v49, v0
	v_mov_b32_e32 v50, v0
	v_mov_b32_e32 v51, v0
	v_mov_b32_e32 v52, v0
	v_mov_b32_e32 v53, v0
	v_mov_b32_e32 v54, v0
	v_mov_b32_e32 v55, v0
	v_mov_b32_e32 v8, v0
	v_mov_b32_e32 v9, v0
	v_mov_b32_e32 v10, v0
	v_mov_b32_e32 v11, v0
	v_mov_b32_e32 v12, v0
	v_mov_b32_e32 v13, v0
	v_mov_b32_e32 v14, v0
	v_mov_b32_e32 v15, v0
	v_mov_b32_e32 v24, v0
	v_mov_b32_e32 v25, v0
	v_mov_b32_e32 v26, v0
	v_mov_b32_e32 v27, v0
	v_mov_b32_e32 v28, v0
	v_mov_b32_e32 v29, v0
	v_mov_b32_e32 v30, v0
	v_mov_b32_e32 v31, v0
	v_mov_b32_e32 v40, v0
	v_mov_b32_e32 v41, v0
	v_mov_b32_e32 v42, v0
	v_mov_b32_e32 v43, v0
	v_mov_b32_e32 v44, v0
	v_mov_b32_e32 v45, v0
	v_mov_b32_e32 v46, v0
	v_mov_b32_e32 v47, v0
	v_mov_b32_e32 v56, v0
	v_mov_b32_e32 v57, v0
	v_mov_b32_e32 v58, v0
	v_mov_b32_e32 v59, v0
	v_mov_b32_e32 v60, v0
	v_mov_b32_e32 v61, v0
	v_mov_b32_e32 v62, v0
	v_mov_b32_e32 v63, v0
	v_mov_b32_e32 v64, v0
	v_mov_b32_e32 v65, v0
	v_mov_b32_e32 v66, v0
	v_mov_b32_e32 v67, v0
	v_mov_b32_e32 v68, v0
	v_mov_b32_e32 v69, v0
	v_mov_b32_e32 v70, v0
	v_mov_b32_e32 v71, v0
	v_mov_b32_e32 v80, v0
	v_mov_b32_e32 v81, v0
	v_mov_b32_e32 v82, v0
	v_mov_b32_e32 v83, v0
	v_mov_b32_e32 v84, v0
	v_mov_b32_e32 v85, v0
	v_mov_b32_e32 v86, v0
	v_mov_b32_e32 v87, v0
	v_mov_b32_e32 v96, v0
	v_mov_b32_e32 v97, v0
	v_mov_b32_e32 v98, v0
	v_mov_b32_e32 v99, v0
	v_mov_b32_e32 v100, v0
	v_mov_b32_e32 v101, v0
	v_mov_b32_e32 v102, v0
	v_mov_b32_e32 v103, v0
	v_mov_b32_e32 v112, v0
	v_mov_b32_e32 v113, v0
	v_mov_b32_e32 v114, v0
	v_mov_b32_e32 v115, v0
	v_mov_b32_e32 v116, v0
	v_mov_b32_e32 v117, v0
	v_mov_b32_e32 v118, v0
	v_mov_b32_e32 v119, v0
	v_mov_b32_e32 v72, v0
	v_mov_b32_e32 v73, v0
	v_mov_b32_e32 v74, v0
	v_mov_b32_e32 v75, v0
	v_mov_b32_e32 v76, v0
	v_mov_b32_e32 v77, v0
	v_mov_b32_e32 v78, v0
	v_mov_b32_e32 v79, v0
	v_mov_b32_e32 v88, v0
	v_mov_b32_e32 v89, v0
	v_mov_b32_e32 v90, v0
	v_mov_b32_e32 v91, v0
	v_mov_b32_e32 v92, v0
	v_mov_b32_e32 v93, v0
	v_mov_b32_e32 v94, v0
	v_mov_b32_e32 v95, v0
	v_mov_b32_e32 v104, v0
	v_mov_b32_e32 v105, v0
	v_mov_b32_e32 v106, v0
	v_mov_b32_e32 v107, v0
	v_mov_b32_e32 v108, v0
	v_mov_b32_e32 v109, v0
	v_mov_b32_e32 v110, v0
	v_mov_b32_e32 v111, v0
	v_mov_b32_e32 v120, v0
	v_mov_b32_e32 v121, v0
	v_mov_b32_e32 v122, v0
	v_mov_b32_e32 v123, v0
	v_mov_b32_e32 v124, v0
	v_mov_b32_e32 v125, v0
	v_mov_b32_e32 v126, v0
	v_mov_b32_e32 v127, v0
	.p2alignl 6, 3212836864

;     ...
;         const bool has_next = S.next(ui + 1, nxt);
;         const char* nA = has_next ? (const char*)g.A + (size_t)nxt.pm * tstep : cA; const char* nB = has_next ? (const char*)g.Bt + (size_t)nxt.pn * tstep : cB;
;     ...
; #pragma unroll
;         for (int a = 0; a < 2; ++a)
; #pragma unroll
;             for (int b = 0; b < 2; ++b)
; #pragma unroll
;                 for (int m = 0; m < 4; ++m)
; #pragma unroll
;                     for (int n = 0; n < 2; ++n) acc[a][b][m][n] = (f32x4){0.f, 0.f, 0.f, 0.f};
;         cur = nxt; cA = nA; cB = nB; ++ui;
.LBB0_1704:
	s_ashr_i32 s61, s60, 31
	s_lshl_b64 s[8:9], s[60:61], 19
	s_add_u32 s62, s29, s8
	s_addc_u32 s63, s72, s9
	s_and_b64 s[8:9], s[12:13], exec
	s_cselect_b32 s8, s63, s69
	s_cselect_b32 s9, s62, s68
	s_ashr_i32 s59, s58, 31
	s_lshl_b64 s[34:35], s[58:59], 19
	s_add_u32 s64, s73, s34
	s_addc_u32 s65, s74, s35
	s_and_b64 s[34:35], s[12:13], exec
	s_cselect_b32 s17, s65, s15
	s_cselect_b32 s20, s64, s14
	s_add_u32 s59, s14, 0x100
	s_addc_u32 s61, s15, 0
	s_add_u32 s14, s68, 0x40080
	v_mov_b32_e32 v0, 0
	s_addc_u32 s15, s69, 0
	s_mov_b32 s67, -2
	v_mov_b32_e32 v1, v0
	v_mov_b32_e32 v2, v0
	v_mov_b32_e32 v3, v0
	v_mov_b32_e32 v4, v0
	v_mov_b32_e32 v5, v0
	v_mov_b32_e32 v6, v0
	v_mov_b32_e32 v7, v0
	v_mov_b32_e32 v16, v0
	v_mov_b32_e32 v17, v0
	v_mov_b32_e32 v18, v0
	v_mov_b32_e32 v19, v0
	v_mov_b32_e32 v20, v0
	v_mov_b32_e32 v21, v0
	v_mov_b32_e32 v22, v0
	v_mov_b32_e32 v23, v0
	v_mov_b32_e32 v32, v0
	v_mov_b32_e32 v33, v0
	v_mov_b32_e32 v34, v0
	v_mov_b32_e32 v35, v0
	v_mov_b32_e32 v36, v0
	v_mov_b32_e32 v37, v0
	v_mov_b32_e32 v38, v0
	v_mov_b32_e32 v39, v0
	v_mov_b32_e32 v48, v0
	v_mov_b32_e32 v49, v0
	v_mov_b32_e32 v50, v0
	v_mov_b32_e32 v51, v0
	v_mov_b32_e32 v52, v0
	v_mov_b32_e32 v53, v0
	v_mov_b32_e32 v54, v0
	v_mov_b32_e32 v55, v0
	v_mov_b32_e32 v8, v0
	v_mov_b32_e32 v9, v0
	v_mov_b32_e32 v10, v0
	v_mov_b32_e32 v11, v0
	v_mov_b32_e32 v12, v0
	v_mov_b32_e32 v13, v0
	v_mov_b32_e32 v14, v0
	v_mov_b32_e32 v15, v0
	v_mov_b32_e32 v24, v0
	v_mov_b32_e32 v25, v0
	v_mov_b32_e32 v26, v0
	v_mov_b32_e32 v27, v0
	v_mov_b32_e32 v28, v0
	v_mov_b32_e32 v29, v0
	v_mov_b32_e32 v30, v0
	v_mov_b32_e32 v31, v0
	v_mov_b32_e32 v40, v0
	v_mov_b32_e32 v41, v0
	v_mov_b32_e32 v42, v0
	v_mov_b32_e32 v43, v0
	v_mov_b32_e32 v44, v0
	v_mov_b32_e32 v45, v0
	v_mov_b32_e32 v46, v0
	v_mov_b32_e32 v47, v0
	v_mov_b32_e32 v56, v0
	v_mov_b32_e32 v57, v0
	v_mov_b32_e32 v58, v0
	v_mov_b32_e32 v59, v0
	v_mov_b32_e32 v60, v0
	v_mov_b32_e32 v61, v0
	v_mov_b32_e32 v62, v0
	v_mov_b32_e32 v63, v0
	v_mov_b32_e32 v64, v0
	v_mov_b32_e32 v65, v0
	v_mov_b32_e32 v66, v0
	v_mov_b32_e32 v67, v0
	v_mov_b32_e32 v68, v0
	v_mov_b32_e32 v69, v0
	v_mov_b32_e32 v70, v0
	v_mov_b32_e32 v71, v0
	v_mov_b32_e32 v80, v0
	v_mov_b32_e32 v81, v0
	v_mov_b32_e32 v82, v0
	v_mov_b32_e32 v83, v0
	v_mov_b32_e32 v84, v0
	v_mov_b32_e32 v85, v0
	v_mov_b32_e32 v86, v0
	v_mov_b32_e32 v87, v0
	v_mov_b32_e32 v96, v0
	v_mov_b32_e32 v97, v0
	v_mov_b32_e32 v98, v0
	v_mov_b32_e32 v99, v0
	v_mov_b32_e32 v100, v0
	v_mov_b32_e32 v101, v0
	v_mov_b32_e32 v102, v0
	v_mov_b32_e32 v103, v0
	v_mov_b32_e32 v112, v0
	v_mov_b32_e32 v113, v0
	v_mov_b32_e32 v114, v0
	v_mov_b32_e32 v115, v0
	v_mov_b32_e32 v116, v0
	v_mov_b32_e32 v117, v0
	v_mov_b32_e32 v118, v0
	v_mov_b32_e32 v119, v0
	v_mov_b32_e32 v72, v0
	v_mov_b32_e32 v73, v0
	v_mov_b32_e32 v74, v0
	v_mov_b32_e32 v75, v0
	v_mov_b32_e32 v76, v0
	v_mov_b32_e32 v77, v0
	v_mov_b32_e32 v78, v0
	v_mov_b32_e32 v79, v0
	v_mov_b32_e32 v88, v0
	v_mov_b32_e32 v89, v0
	v_mov_b32_e32 v90, v0
	v_mov_b32_e32 v91, v0
	v_mov_b32_e32 v92, v0
	v_mov_b32_e32 v93, v0
	v_mov_b32_e32 v94, v0
	v_mov_b32_e32 v95, v0
	v_mov_b32_e32 v104, v0
	v_mov_b32_e32 v105, v0
	v_mov_b32_e32 v106, v0
	v_mov_b32_e32 v107, v0
	v_mov_b32_e32 v108, v0
	v_mov_b32_e32 v109, v0
	v_mov_b32_e32 v110, v0
	v_mov_b32_e32 v111, v0
	v_mov_b32_e32 v120, v0
	v_mov_b32_e32 v121, v0
	v_mov_b32_e32 v122, v0
	v_mov_b32_e32 v123, v0
	v_mov_b32_e32 v124, v0
	v_mov_b32_e32 v125, v0
	v_mov_b32_e32 v126, v0
	v_mov_b32_e32 v127, v0
	.p2alignl 6, 3212836864

;     ...
;         const bool has_next = S.next(ui + 1, nxt);
;         const char* nA = has_next ? (const char*)g.A + (size_t)nxt.pm * tstep : cA; const char* nB = has_next ? (const char*)g.Bt + (size_t)nxt.pn * tstep : cB;
;     ...
; #pragma unroll
;         for (int a = 0; a < 2; ++a)
; #pragma unroll
;             for (int b = 0; b < 2; ++b)
; #pragma unroll
;                 for (int m = 0; m < 4; ++m)
; #pragma unroll
;                     for (int n = 0; n < 2; ++n) acc[a][b][m][n] = (f32x4){0.f, 0.f, 0.f, 0.f};
;         cur = nxt; cA = nA; cB = nB; ++ui;
.LBB0_2333:
	s_ashr_i32 s19, s18, 31
	s_lshl_b64 s[20:21], s[18:19], 19
	s_add_u32 s20, s44, s20
	s_addc_u32 s21, s45, s21
	s_and_b64 s[22:23], s[6:7], exec
	s_cselect_b32 s19, s21, s37
	s_cselect_b32 s65, s20, s36
	s_ashr_i32 s17, s16, 31
	s_lshl_b64 s[22:23], s[16:17], 19
	s_add_u32 s22, s46, s22
	s_addc_u32 s23, s47, s23
	s_and_b64 s[34:35], s[6:7], exec
	s_cselect_b32 s17, s23, s39
	s_cselect_b32 s66, s22, s38
	s_add_u32 s67, s38, 0x100
	v_mov_b32_e32 v0, 0
	s_addc_u32 s68, s39, 0
	s_mov_b32 s69, -2
	v_mov_b32_e32 v1, v0
	v_mov_b32_e32 v2, v0
	v_mov_b32_e32 v3, v0
	v_mov_b32_e32 v4, v0
	v_mov_b32_e32 v5, v0
	v_mov_b32_e32 v6, v0
	v_mov_b32_e32 v7, v0
	v_mov_b32_e32 v16, v0
	v_mov_b32_e32 v17, v0
	v_mov_b32_e32 v18, v0
	v_mov_b32_e32 v19, v0
	v_mov_b32_e32 v20, v0
	v_mov_b32_e32 v21, v0
	v_mov_b32_e32 v22, v0
	v_mov_b32_e32 v23, v0
	v_mov_b32_e32 v32, v0
	v_mov_b32_e32 v33, v0
	v_mov_b32_e32 v34, v0
	v_mov_b32_e32 v35, v0
	v_mov_b32_e32 v36, v0
	v_mov_b32_e32 v37, v0
	v_mov_b32_e32 v38, v0
	v_mov_b32_e32 v39, v0
	v_mov_b32_e32 v48, v0
	v_mov_b32_e32 v49, v0
	v_mov_b32_e32 v50, v0
	v_mov_b32_e32 v51, v0
	v_mov_b32_e32 v52, v0
	v_mov_b32_e32 v53, v0
	v_mov_b32_e32 v54, v0
	v_mov_b32_e32 v55, v0
	v_mov_b32_e32 v8, v0
	v_mov_b32_e32 v9, v0
	v_mov_b32_e32 v10, v0
	v_mov_b32_e32 v11, v0
	v_mov_b32_e32 v12, v0
	v_mov_b32_e32 v13, v0
	v_mov_b32_e32 v14, v0
	v_mov_b32_e32 v15, v0
	v_mov_b32_e32 v24, v0
	v_mov_b32_e32 v25, v0
	v_mov_b32_e32 v26, v0
	v_mov_b32_e32 v27, v0
	v_mov_b32_e32 v28, v0
	v_mov_b32_e32 v29, v0
	v_mov_b32_e32 v30, v0
	v_mov_b32_e32 v31, v0
	v_mov_b32_e32 v40, v0
	v_mov_b32_e32 v41, v0
	v_mov_b32_e32 v42, v0
	v_mov_b32_e32 v43, v0
	v_mov_b32_e32 v44, v0
	v_mov_b32_e32 v45, v0
	v_mov_b32_e32 v46, v0
	v_mov_b32_e32 v47, v0
	v_mov_b32_e32 v56, v0
	v_mov_b32_e32 v57, v0
	v_mov_b32_e32 v58, v0
	v_mov_b32_e32 v59, v0
	v_mov_b32_e32 v60, v0
	v_mov_b32_e32 v61, v0
	v_mov_b32_e32 v62, v0
	v_mov_b32_e32 v63, v0
	v_mov_b32_e32 v64, v0
	v_mov_b32_e32 v65, v0
	v_mov_b32_e32 v66, v0
	v_mov_b32_e32 v67, v0
	v_mov_b32_e32 v68, v0
	v_mov_b32_e32 v69, v0
	v_mov_b32_e32 v70, v0
	v_mov_b32_e32 v71, v0
	v_mov_b32_e32 v80, v0
	v_mov_b32_e32 v81, v0
	v_mov_b32_e32 v82, v0
	v_mov_b32_e32 v83, v0
	v_mov_b32_e32 v84, v0
	v_mov_b32_e32 v85, v0
	v_mov_b32_e32 v86, v0
	v_mov_b32_e32 v87, v0
	v_mov_b32_e32 v96, v0
	v_mov_b32_e32 v97, v0
	v_mov_b32_e32 v98, v0
	v_mov_b32_e32 v99, v0
	v_mov_b32_e32 v100, v0
	v_mov_b32_e32 v101, v0
	v_mov_b32_e32 v102, v0
	v_mov_b32_e32 v103, v0
	v_mov_b32_e32 v112, v0
	v_mov_b32_e32 v113, v0
	v_mov_b32_e32 v114, v0
	v_mov_b32_e32 v115, v0
	v_mov_b32_e32 v116, v0
	v_mov_b32_e32 v117, v0
	v_mov_b32_e32 v118, v0
	v_mov_b32_e32 v119, v0
	v_mov_b32_e32 v72, v0
	v_mov_b32_e32 v73, v0
	v_mov_b32_e32 v74, v0
	v_mov_b32_e32 v75, v0
	v_mov_b32_e32 v76, v0
	v_mov_b32_e32 v77, v0
	v_mov_b32_e32 v78, v0
	v_mov_b32_e32 v79, v0
	v_mov_b32_e32 v88, v0
	v_mov_b32_e32 v89, v0
	v_mov_b32_e32 v90, v0
	v_mov_b32_e32 v91, v0
	v_mov_b32_e32 v92, v0
	v_mov_b32_e32 v93, v0
	v_mov_b32_e32 v94, v0
	v_mov_b32_e32 v95, v0
	v_mov_b32_e32 v104, v0
	v_mov_b32_e32 v105, v0
	v_mov_b32_e32 v106, v0
	v_mov_b32_e32 v107, v0
	v_mov_b32_e32 v108, v0
	v_mov_b32_e32 v109, v0
	v_mov_b32_e32 v110, v0
	v_mov_b32_e32 v111, v0
	v_mov_b32_e32 v120, v0
	v_mov_b32_e32 v121, v0
	v_mov_b32_e32 v122, v0
	v_mov_b32_e32 v123, v0
	v_mov_b32_e32 v124, v0
	v_mov_b32_e32 v125, v0
	v_mov_b32_e32 v126, v0
	v_mov_b32_e32 v127, v0
	.p2alignl 6, 3212836864

;     ...
;         const bool has_next = S.next(ui + 1, nxt);
;         const char* nA = has_next ? (const char*)g.A + (size_t)nxt.pm * tstep : cA; const char* nB = has_next ? (const char*)g.Bt + (size_t)nxt.pn * tstep : cB;
;     ...
; #pragma unroll
;         for (int a = 0; a < 2; ++a)
; #pragma unroll
;             for (int b = 0; b < 2; ++b)
; #pragma unroll
;                 for (int m = 0; m < 4; ++m)
; #pragma unroll
;                     for (int n = 0; n < 2; ++n) acc[a][b][m][n] = (f32x4){0.f, 0.f, 0.f, 0.f};
;         cur = nxt; cA = nA; cB = nB; ++ui;
.LBB0_2460:
	s_ashr_i32 s19, s18, 31
	s_lshl_b64 s[20:21], s[18:19], 19
	s_add_u32 s20, s29, s20
	s_addc_u32 s21, s42, s21
	s_and_b64 s[22:23], s[6:7], exec
	s_cselect_b32 s19, s21, s39
	s_cselect_b32 s59, s20, s38
	s_ashr_i32 s17, s16, 31
	s_lshl_b64 s[22:23], s[16:17], 19
	s_add_u32 s22, s43, s22
	s_addc_u32 s23, s44, s23
	s_and_b64 s[34:35], s[6:7], exec
	s_cselect_b32 s17, s23, s37
	s_cselect_b32 s60, s22, s36
	s_add_u32 s61, s36, 0x100
	s_addc_u32 s62, s37, 0
	s_add_u32 s36, s38, 0x40080
	v_mov_b32_e32 v0, 0
	s_addc_u32 s37, s39, 0
	s_mov_b32 s63, -2
	v_mov_b32_e32 v1, v0
	v_mov_b32_e32 v2, v0
	v_mov_b32_e32 v3, v0
	v_mov_b32_e32 v4, v0
	v_mov_b32_e32 v5, v0
	v_mov_b32_e32 v6, v0
	v_mov_b32_e32 v7, v0
	v_mov_b32_e32 v16, v0
	v_mov_b32_e32 v17, v0
	v_mov_b32_e32 v18, v0
	v_mov_b32_e32 v19, v0
	v_mov_b32_e32 v20, v0
	v_mov_b32_e32 v21, v0
	v_mov_b32_e32 v22, v0
	v_mov_b32_e32 v23, v0
	v_mov_b32_e32 v32, v0
	v_mov_b32_e32 v33, v0
	v_mov_b32_e32 v34, v0
	v_mov_b32_e32 v35, v0
	v_mov_b32_e32 v36, v0
	v_mov_b32_e32 v37, v0
	v_mov_b32_e32 v38, v0
	v_mov_b32_e32 v39, v0
	v_mov_b32_e32 v48, v0
	v_mov_b32_e32 v49, v0
	v_mov_b32_e32 v50, v0
	v_mov_b32_e32 v51, v0
	v_mov_b32_e32 v52, v0
	v_mov_b32_e32 v53, v0
	v_mov_b32_e32 v54, v0
	v_mov_b32_e32 v55, v0
	v_mov_b32_e32 v8, v0
	v_mov_b32_e32 v9, v0
	v_mov_b32_e32 v10, v0
	v_mov_b32_e32 v11, v0
	v_mov_b32_e32 v12, v0
	v_mov_b32_e32 v13, v0
	v_mov_b32_e32 v14, v0
	v_mov_b32_e32 v15, v0
	v_mov_b32_e32 v24, v0
	v_mov_b32_e32 v25, v0
	v_mov_b32_e32 v26, v0
	v_mov_b32_e32 v27, v0
	v_mov_b32_e32 v28, v0
	v_mov_b32_e32 v29, v0
	v_mov_b32_e32 v30, v0
	v_mov_b32_e32 v31, v0
	v_mov_b32_e32 v40, v0
	v_mov_b32_e32 v41, v0
	v_mov_b32_e32 v42, v0
	v_mov_b32_e32 v43, v0
	v_mov_b32_e32 v44, v0
	v_mov_b32_e32 v45, v0
	v_mov_b32_e32 v46, v0
	v_mov_b32_e32 v47, v0
	v_mov_b32_e32 v56, v0
	v_mov_b32_e32 v57, v0
	v_mov_b32_e32 v58, v0
	v_mov_b32_e32 v59, v0
	v_mov_b32_e32 v60, v0
	v_mov_b32_e32 v61, v0
	v_mov_b32_e32 v62, v0
	v_mov_b32_e32 v63, v0
	v_mov_b32_e32 v64, v0
	v_mov_b32_e32 v65, v0
	v_mov_b32_e32 v66, v0
	v_mov_b32_e32 v67, v0
	v_mov_b32_e32 v68, v0
	v_mov_b32_e32 v69, v0
	v_mov_b32_e32 v70, v0
	v_mov_b32_e32 v71, v0
	v_mov_b32_e32 v80, v0
	v_mov_b32_e32 v81, v0
	v_mov_b32_e32 v82, v0
	v_mov_b32_e32 v83, v0
	v_mov_b32_e32 v84, v0
	v_mov_b32_e32 v85, v0
	v_mov_b32_e32 v86, v0
	v_mov_b32_e32 v87, v0
	v_mov_b32_e32 v96, v0
	v_mov_b32_e32 v97, v0
	v_mov_b32_e32 v98, v0
	v_mov_b32_e32 v99, v0
	v_mov_b32_e32 v100, v0
	v_mov_b32_e32 v101, v0
	v_mov_b32_e32 v102, v0
	v_mov_b32_e32 v103, v0
	v_mov_b32_e32 v112, v0
	v_mov_b32_e32 v113, v0
	v_mov_b32_e32 v114, v0
	v_mov_b32_e32 v115, v0
	v_mov_b32_e32 v116, v0
	v_mov_b32_e32 v117, v0
	v_mov_b32_e32 v118, v0
	v_mov_b32_e32 v119, v0
	v_mov_b32_e32 v72, v0
	v_mov_b32_e32 v73, v0
	v_mov_b32_e32 v74, v0
	v_mov_b32_e32 v75, v0
	v_mov_b32_e32 v76, v0
	v_mov_b32_e32 v77, v0
	v_mov_b32_e32 v78, v0
	v_mov_b32_e32 v79, v0
	v_mov_b32_e32 v88, v0
	v_mov_b32_e32 v89, v0
	v_mov_b32_e32 v90, v0
	v_mov_b32_e32 v91, v0
	v_mov_b32_e32 v92, v0
	v_mov_b32_e32 v93, v0
	v_mov_b32_e32 v94, v0
	v_mov_b32_e32 v95, v0
	v_mov_b32_e32 v104, v0
	v_mov_b32_e32 v105, v0
	v_mov_b32_e32 v106, v0
	v_mov_b32_e32 v107, v0
	v_mov_b32_e32 v108, v0
	v_mov_b32_e32 v109, v0
	v_mov_b32_e32 v110, v0
	v_mov_b32_e32 v111, v0
	v_mov_b32_e32 v120, v0
	v_mov_b32_e32 v121, v0
	v_mov_b32_e32 v122, v0
	v_mov_b32_e32 v123, v0
	v_mov_b32_e32 v124, v0
	v_mov_b32_e32 v125, v0
	v_mov_b32_e32 v126, v0
	v_mov_b32_e32 v127, v0
	.p2alignl 6, 3212836864

;     ...
; #pragma unroll
;         for (int a = 0; a < 2; ++a)
; #pragma unroll
;             for (int b = 0; b < 2; ++b)
; #pragma unroll
;                 for (int m = 0; m < 4; ++m)
; #pragma unroll
;                     for (int n = 0; n < 2; ++n) acc[a][b][m][n] = (f32x4){0.f, 0.f, 0.f, 0.f};
;         cur = nxt; cA = nA; cB = nB; ++ui;
.LBB0_2540:
	s_add_u32 s59, s20, 0x100
	v_mov_b32_e32 v0, 0
	s_addc_u32 s60, s21, 0
	s_mov_b32 s61, -2
	v_mov_b32_e32 v1, v0
	v_mov_b32_e32 v2, v0
	v_mov_b32_e32 v3, v0
	v_mov_b32_e32 v4, v0
	v_mov_b32_e32 v5, v0
	v_mov_b32_e32 v6, v0
	v_mov_b32_e32 v7, v0
	v_mov_b32_e32 v16, v0
	v_mov_b32_e32 v17, v0
	v_mov_b32_e32 v18, v0
	v_mov_b32_e32 v19, v0
	v_mov_b32_e32 v20, v0
	v_mov_b32_e32 v21, v0
	v_mov_b32_e32 v22, v0
	v_mov_b32_e32 v23, v0
	v_mov_b32_e32 v32, v0
	v_mov_b32_e32 v33, v0
	v_mov_b32_e32 v34, v0
	v_mov_b32_e32 v35, v0
	v_mov_b32_e32 v36, v0
	v_mov_b32_e32 v37, v0
	v_mov_b32_e32 v38, v0
	v_mov_b32_e32 v39, v0
	v_mov_b32_e32 v48, v0
	v_mov_b32_e32 v49, v0
	v_mov_b32_e32 v50, v0
	v_mov_b32_e32 v51, v0
	v_mov_b32_e32 v52, v0
	v_mov_b32_e32 v53, v0
	v_mov_b32_e32 v54, v0
	v_mov_b32_e32 v55, v0
	v_mov_b32_e32 v8, v0
	v_mov_b32_e32 v9, v0
	v_mov_b32_e32 v10, v0
	v_mov_b32_e32 v11, v0
	v_mov_b32_e32 v12, v0
	v_mov_b32_e32 v13, v0
	v_mov_b32_e32 v14, v0
	v_mov_b32_e32 v15, v0
	v_mov_b32_e32 v24, v0
	v_mov_b32_e32 v25, v0
	v_mov_b32_e32 v26, v0
	v_mov_b32_e32 v27, v0
	v_mov_b32_e32 v28, v0
	v_mov_b32_e32 v29, v0
	v_mov_b32_e32 v30, v0
	v_mov_b32_e32 v31, v0
	v_mov_b32_e32 v40, v0
	v_mov_b32_e32 v41, v0
	v_mov_b32_e32 v42, v0
	v_mov_b32_e32 v43, v0
	v_mov_b32_e32 v44, v0
	v_mov_b32_e32 v45, v0
	v_mov_b32_e32 v46, v0
	v_mov_b32_e32 v47, v0
	v_mov_b32_e32 v56, v0
	v_mov_b32_e32 v57, v0
	v_mov_b32_e32 v58, v0
	v_mov_b32_e32 v59, v0
	v_mov_b32_e32 v60, v0
	v_mov_b32_e32 v61, v0
	v_mov_b32_e32 v62, v0
	v_mov_b32_e32 v63, v0
	v_mov_b32_e32 v64, v0
	v_mov_b32_e32 v65, v0
	v_mov_b32_e32 v66, v0
	v_mov_b32_e32 v67, v0
	v_mov_b32_e32 v68, v0
	v_mov_b32_e32 v69, v0
	v_mov_b32_e32 v70, v0
	v_mov_b32_e32 v71, v0
	v_mov_b32_e32 v80, v0
	v_mov_b32_e32 v81, v0
	v_mov_b32_e32 v82, v0
	v_mov_b32_e32 v83, v0
	v_mov_b32_e32 v84, v0
	v_mov_b32_e32 v85, v0
	v_mov_b32_e32 v86, v0
	v_mov_b32_e32 v87, v0
	v_mov_b32_e32 v96, v0
	v_mov_b32_e32 v97, v0
	v_mov_b32_e32 v98, v0
	v_mov_b32_e32 v99, v0
	v_mov_b32_e32 v100, v0
	v_mov_b32_e32 v101, v0
	v_mov_b32_e32 v102, v0
	v_mov_b32_e32 v103, v0
	v_mov_b32_e32 v112, v0
	v_mov_b32_e32 v113, v0
	v_mov_b32_e32 v114, v0
	v_mov_b32_e32 v115, v0
	v_mov_b32_e32 v116, v0
	v_mov_b32_e32 v117, v0
	v_mov_b32_e32 v118, v0
	v_mov_b32_e32 v119, v0
	v_mov_b32_e32 v72, v0
	v_mov_b32_e32 v73, v0
	v_mov_b32_e32 v74, v0
	v_mov_b32_e32 v75, v0
	v_mov_b32_e32 v76, v0
	v_mov_b32_e32 v77, v0
	v_mov_b32_e32 v78, v0
	v_mov_b32_e32 v79, v0
	v_mov_b32_e32 v88, v0
	v_mov_b32_e32 v89, v0
	v_mov_b32_e32 v90, v0
	v_mov_b32_e32 v91, v0
	v_mov_b32_e32 v92, v0
	v_mov_b32_e32 v93, v0
	v_mov_b32_e32 v94, v0
	v_mov_b32_e32 v95, v0
	v_mov_b32_e32 v104, v0
	v_mov_b32_e32 v105, v0
	v_mov_b32_e32 v106, v0
	v_mov_b32_e32 v107, v0
	v_mov_b32_e32 v108, v0
	v_mov_b32_e32 v109, v0
	v_mov_b32_e32 v110, v0
	v_mov_b32_e32 v111, v0
	v_mov_b32_e32 v120, v0
	v_mov_b32_e32 v121, v0
	v_mov_b32_e32 v122, v0
	v_mov_b32_e32 v123, v0
	v_mov_b32_e32 v124, v0
	v_mov_b32_e32 v125, v0
	v_mov_b32_e32 v126, v0
	v_mov_b32_e32 v127, v0
	.p2alignl 6, 3212836864
